# pass-0 GLA unit: V^T-image loads issued first at the top of the unit as in pass 1
# baseline (speedup 1.0000x reference)
; template <int PASS>
; __device__ __forceinline__ void gla_unit(LAS unsigned char* lds, int ch, int h, const bf16* PROJ, const bf16* GT, bf16* STG, float* DECG, bf16* OMIX, const float* gla_norm) {
;     ...
;         const int kk = tid & 63, qt = (tid >> 6) & 3, d = tid >> 8;
;         const bf16* gp = GT + ((size_t)d * MALL + m0 + 16 * qt) * 256 + h * 64 + kk;
;         const bf16* qp = PROJ + (m0 + 16 * qt) * LDP + PQ + h * 64 + kk; const bf16* kp = PROJ + (m0 + 16 * qt) * LDP + PK + h * 64 + kk;
;         float c[16], kv[16], qv[16];
; #pragma unroll
;         for (int jj = 0; jj < 16; ++jj) { c[jj] = bf1(gp[(size_t)jj * 256]); kv[jj] = bf1(kp[(size_t)jj * LDP]); if (PASS == 1) qv[jj] = bf1(qp[(size_t)jj * LDP]); }
;     ...
;         { const int vcol = tid & 127, q4 = tid >> 7; const bf16* vp = PROJ + (m0 + 16 * q4) * LDP + PV + h * 128 + vcol; unsigned vv[16];
; #pragma unroll
;           for (int jj = 0; jj < 16; ++jj) vv[jj] = vp[(size_t)jj * LDP];
.LBB0_604:
	s_and_b64 vcc, exec, s[0:1]
	s_cbranch_vccz .LBB0_561
	s_ashr_i32 s58, s88, 2
	v_mov_b32_e32 v48, v0
	s_ashr_i32 s59, s58, 31
	v_ashrrev_i32_e32 v36, 6, v48
	v_ashrrev_i32_e32 v49, 8, v48
	s_lshl_b64 s[6:7], s[58:59], 6
	v_mov_b32_e32 v145, 0
	v_ashrrev_i32_e32 v158, 7, v48
	v_lshlrev_b32_e32 v224, 4, v158
	v_ashrrev_i32_e32 v225, 31, v224
	v_lshl_add_u64 v[224:225], s[6:7], 0, v[224:225]
	v_mov_b64_e32 v[226:227], s[56:57]
	v_and_b32_e32 v159, 0x7f, v48
	v_mad_u64_u32 v[226:227], s[100:101], v224, s73, v[226:227]
	v_mad_i32_i24 v227, v225, s73, v227
	v_lshlrev_b32_e32 v144, 1, v159
	v_lshl_add_u64 v[224:225], v[226:227], 0, v[144:145]
	v_add_co_u32_e64 v226, s[98:99], s61, v224
	s_mov_b32 s100, 0x15000
	s_nop 0
	v_addc_co_u32_e64 v227, s[98:99], 0, v225, s[98:99]
	v_add_co_u32_e64 v228, s[98:99], s65, v224
	s_nop 1
	v_addc_co_u32_e64 v229, s[98:99], 0, v225, s[98:99]
	v_add_co_u32_e64 v230, s[98:99], s66, v224
	s_nop 1
	v_addc_co_u32_e64 v231, s[98:99], 0, v225, s[98:99]
	v_add_co_u32_e64 v232, s[98:99], s67, v224
	s_nop 1
	v_addc_co_u32_e64 v233, s[98:99], 0, v225, s[98:99]
	v_add_co_u32_e64 v234, s[98:99], s68, v224
	s_nop 1
	v_addc_co_u32_e64 v235, s[98:99], 0, v225, s[98:99]
	v_add_co_u32_e64 v236, s[98:99], s69, v224
	s_nop 1
	v_addc_co_u32_e64 v237, s[98:99], 0, v225, s[98:99]
	v_add_co_u32_e64 v238, s[98:99], s71, v224
	s_nop 1
	v_addc_co_u32_e64 v239, s[98:99], 0, v225, s[98:99]
	global_load_ushort v160, v[224:225], off offset:1024
	global_load_ushort v161, v[226:227], off offset:2688
	global_load_ushort v162, v[228:229], off offset:256
	global_load_ushort v163, v[230:231], off offset:1920
	global_load_ushort v164, v[232:233], off offset:3584
	global_load_ushort v165, v[234:235], off offset:1152
	global_load_ushort v166, v[236:237], off offset:2816
	global_load_ushort v167, v[238:239], off offset:384
	v_add_co_u32_e64 v226, s[98:99], s72, v224
	s_nop 1
	v_addc_co_u32_e64 v227, s[98:99], 0, v225, s[98:99]
	v_add_co_u32_e64 v228, s[98:99], s74, v224
	s_nop 1
	v_addc_co_u32_e64 v229, s[98:99], 0, v225, s[98:99]
	v_add_co_u32_e64 v230, s[98:99], s75, v224
	s_nop 1
	v_addc_co_u32_e64 v231, s[98:99], 0, v225, s[98:99]
	v_add_co_u32_e64 v232, s[98:99], s80, v224
	s_nop 1
	v_addc_co_u32_e64 v233, s[98:99], 0, v225, s[98:99]
	v_add_co_u32_e64 v234, s[98:99], s81, v224
	s_nop 1
	v_addc_co_u32_e64 v235, s[98:99], 0, v225, s[98:99]
	v_add_co_u32_e64 v236, s[98:99], s82, v224
	s_nop 1
	v_addc_co_u32_e64 v237, s[98:99], 0, v225, s[98:99]
	v_add_co_u32_e64 v238, s[98:99], s83, v224
	s_nop 1
	v_addc_co_u32_e64 v239, s[98:99], 0, v225, s[98:99]
	v_add_co_u32_e64 v224, s[98:99], s100, v224
	s_nop 0
	s_nop 0
	v_addc_co_u32_e64 v225, s[98:99], 0, v225, s[98:99]
	global_load_ushort v168, v[226:227], off offset:2048
	global_load_ushort v169, v[228:229], off offset:3712
	global_load_ushort v170, v[230:231], off offset:1280
	global_load_ushort v171, v[232:233], off offset:2944
	global_load_ushort v172, v[234:235], off offset:512
	global_load_ushort v173, v[236:237], off offset:2176
	global_load_ushort v174, v[238:239], off offset:3840
	s_nop 0
	global_load_ushort v175, v[224:225], off offset:1408
	v_and_b32_e32 v51, 3, v36
	v_mul_hi_i32_i24_e32 v5, 0x4400, v49
	v_mul_i32_i24_e32 v4, 0x4400, v49
	v_lshl_add_u64 v[4:5], v[4:5], 0, s[6:7]
	v_lshlrev_b32_e32 v6, 4, v51
	v_or_b32_e32 v4, v4, v6
	v_or_b32_e32 v8, s6, v6
	v_mov_b64_e32 v[6:7], s[54:55]
	v_and_b32_e32 v50, 63, v48
	v_mad_u64_u32 v[6:7], s[0:1], v8, s73, v[6:7]
	v_lshlrev_b32_e32 v2, 1, v50
	v_mad_i32_i24 v7, s7, v1, v7
	v_lshl_add_u64 v[6:7], v[6:7], 0, v[2:3]
	v_add_co_u32_e32 v8, vcc, s61, v6
	v_lshlrev_b64 v[4:5], 9, v[4:5]
	s_nop 0
	v_addc_co_u32_e32 v9, vcc, 0, v7, vcc
	v_add_co_u32_e32 v10, vcc, s62, v6
	v_lshl_add_u64 v[4:5], s[44:45], 0, v[4:5]
	s_nop 0
	v_addc_co_u32_e32 v11, vcc, 0, v7, vcc
	v_add_co_u32_e32 v12, vcc, s66, v6
	v_lshl_add_u64 v[4:5], v[4:5], 0, v[2:3]
	s_nop 0
	v_addc_co_u32_e32 v13, vcc, 0, v7, vcc
	v_add_co_u32_e32 v14, vcc, s67, v6
	global_load_ushort v2, v[4:5], off
	global_load_ushort v37, v[4:5], off offset:512
	global_load_ushort v38, v[4:5], off offset:1024
	global_load_ushort v39, v[4:5], off offset:1536
	global_load_ushort v40, v[4:5], off offset:2048
	global_load_ushort v41, v[4:5], off offset:2560
	global_load_ushort v42, v[4:5], off offset:3072
	global_load_ushort v43, v[4:5], off offset:3584
	v_addc_co_u32_e32 v15, vcc, 0, v7, vcc
	v_add_co_u32_e32 v16, vcc, s68, v6
	s_movk_i32 s0, 0x100
	s_nop 0
	v_addc_co_u32_e32 v17, vcc, 0, v7, vcc
	v_add_co_u32_e32 v18, vcc, s69, v6
	v_readfirstlane_b32 s26, v36
	s_nop 0
	v_addc_co_u32_e32 v19, vcc, 0, v7, vcc
	v_add_co_u32_e32 v20, vcc, s70, v6
	v_cmp_gt_u32_e64 s[4:5], s0, v48
	s_nop 0
	v_addc_co_u32_e32 v21, vcc, 0, v7, vcc
	v_add_co_u32_e32 v22, vcc, s72, v6
	s_waitcnt vmcnt(5)
; template <int PASS>
; __device__ __forceinline__ void gla_unit(LAS unsigned char* lds, int ch, int h, const bf16* PROJ, const bf16* GT, bf16* STG, float* DECG, bf16* OMIX, const float* gla_norm) {
;     ...
;         for (int jj = 0; jj < 16; ++jj) { c[jj] = bf1(gp[(size_t)jj * 256]); kv[jj] = bf1(kp[(size_t)jj * LDP]); if (PASS == 1) qv[jj] = bf1(qp[(size_t)jj * LDP]); }
;         if (d == 0) {
; #pragma unroll
;             for (int jj = 1; jj < 16; ++jj) c[jj] += c[jj - 1];
;         } else {
; #pragma unroll
	v_lshlrev_b32_e32 v36, 16, v38
	v_addc_co_u32_e32 v23, vcc, 0, v7, vcc
	v_add_co_u32_e32 v4, vcc, s61, v4
	s_waitcnt vmcnt(3)
	v_lshlrev_b32_e32 v38, 16, v40
	v_addc_co_u32_e32 v5, vcc, 0, v5, vcc
	v_add_co_u32_e32 v24, vcc, s74, v6
	global_load_ushort v52, v[22:23], off offset:1536
	global_load_ushort v44, v[4:5], off
	global_load_ushort v45, v[4:5], off offset:512
	global_load_ushort v46, v[4:5], off offset:1024
	global_load_ushort v47, v[4:5], off offset:1536
	global_load_ushort v68, v[4:5], off offset:2048
	global_load_ushort v69, v[4:5], off offset:2560
	global_load_ushort v70, v[4:5], off offset:3072
	v_addc_co_u32_e32 v25, vcc, 0, v7, vcc
	v_add_co_u32_e32 v26, vcc, s75, v6
	s_waitcnt vmcnt(9)
	v_lshlrev_b32_e32 v40, 16, v42
	v_addc_co_u32_e32 v27, vcc, 0, v7, vcc
	v_add_co_u32_e32 v28, vcc, s80, v6
	s_waitcnt vmcnt(6)
	v_lshlrev_b32_e32 v42, 16, v44
	v_addc_co_u32_e32 v29, vcc, 0, v7, vcc
	v_add_co_u32_e32 v30, vcc, s81, v6
	s_waitcnt vmcnt(4)
	v_lshlrev_b32_e32 v44, 16, v46
	v_addc_co_u32_e32 v31, vcc, 0, v7, vcc
	v_add_co_u32_e32 v32, vcc, s82, v6
	s_waitcnt vmcnt(2)
	v_lshlrev_b32_e32 v46, 16, v68
	v_addc_co_u32_e32 v33, vcc, 0, v7, vcc
	v_add_co_u32_e32 v34, vcc, s83, v6
	s_nop 1
	v_addc_co_u32_e32 v35, vcc, 0, v7, vcc
	v_add_co_u32_e32 v22, vcc, 0x15000, v6
	s_nop 1
	v_addc_co_u32_e32 v23, vcc, 0, v7, vcc
	global_load_ushort v59, v[24:25], off offset:3200
	global_load_ushort v57, v[26:27], off offset:768
	global_load_ushort v58, v[28:29], off offset:2432
	global_load_ushort v53, v[30:31], off
	global_load_ushort v55, v[32:33], off offset:1664
	global_load_ushort v54, v[34:35], off offset:3328
	global_load_ushort v56, v[22:23], off offset:896
	s_nop 0
	global_load_ushort v4, v[4:5], off offset:3584
	s_nop 0
	global_load_ushort v65, v[6:7], off offset:512
	global_load_ushort v67, v[8:9], off offset:2176
	global_load_ushort v63, v[10:11], off offset:3840
	global_load_ushort v66, v[12:13], off offset:1408
	global_load_ushort v61, v[14:15], off offset:3072
	global_load_ushort v64, v[16:17], off offset:640
	global_load_ushort v60, v[18:19], off offset:2304
	global_load_ushort v62, v[20:21], off offset:3968
	v_lshlrev_b32_e32 v7, 16, v37
	v_lshlrev_b32_e32 v6, 16, v2
	v_lshlrev_b32_e32 v37, 16, v39
	v_lshlrev_b32_e32 v39, 16, v41
	v_lshlrev_b32_e32 v41, 16, v43
	v_lshlrev_b32_e32 v43, 16, v45
	v_lshlrev_b32_e32 v45, 16, v47
	s_waitcnt vmcnt(17)
	v_lshlrev_b32_e32 v47, 16, v69
	s_waitcnt vmcnt(16)
	v_lshlrev_b32_e32 v8, 16, v70
	v_cmp_lt_u32_e32 vcc, s84, v48
	s_waitcnt vmcnt(8)
	v_lshlrev_b32_e32 v9, 16, v4
	s_and_saveexec_b64 s[0:1], s[4:5]
	s_xor_b64 s[0:1], exec, s[0:1]
	s_cbranch_execz .LBB0_607
	v_pk_add_f32 v[34:35], v[6:7], v[6:7] op_sel:[1,0] op_sel_hi:[0,1]
	v_pk_add_f32 v[32:33], v[34:35], v[36:37]
	s_nop 0
	v_pk_add_f32 v[30:31], v[32:33], v[36:37] op_sel:[0,1] op_sel_hi:[1,0]
	s_nop 0
	v_pk_add_f32 v[28:29], v[30:31], v[38:39]
	s_nop 0
	v_pk_add_f32 v[26:27], v[28:29], v[38:39] op_sel:[0,1] op_sel_hi:[1,0]
	s_nop 0
	v_pk_add_f32 v[24:25], v[26:27], v[40:41]
	s_nop 0
	v_pk_add_f32 v[22:23], v[24:25], v[40:41] op_sel:[0,1] op_sel_hi:[1,0]
	s_nop 0
	v_pk_add_f32 v[20:21], v[22:23], v[42:43]
	s_nop 0
	v_pk_add_f32 v[18:19], v[20:21], v[42:43] op_sel:[0,1] op_sel_hi:[1,0]
	s_nop 0
	v_pk_add_f32 v[16:17], v[18:19], v[44:45]
	s_nop 0
	v_pk_add_f32 v[14:15], v[16:17], v[44:45] op_sel:[0,1] op_sel_hi:[1,0]
	s_nop 0
	v_pk_add_f32 v[12:13], v[14:15], v[46:47]
	s_nop 0
	v_pk_add_f32 v[10:11], v[12:13], v[46:47] op_sel:[0,1] op_sel_hi:[1,0]
	s_nop 0
	v_pk_add_f32 v[4:5], v[10:11], v[8:9]
	s_nop 0
	v_pk_add_f32 v[8:9], v[4:5], v[8:9] op_sel:[0,1] op_sel_hi:[1,0]
	s_nop 0
	v_mov_b32_e32 v9, v8

; #define LAS __attribute__((address_space(3)))
; template <int PASS>
; __device__ __forceinline__ void gla_unit(LAS unsigned char* lds, int ch, int h, const bf16* PROJ, const bf16* GT, bf16* STG, float* DECG, bf16* OMIX, const float* gla_norm) {
;     ...
;         OFFS[(d * 4 + qt) * 64 + kk] = d ? c[0] : c[15];
;         { const int vcol = tid & 127, q4 = tid >> 7; const bf16* vp = PROJ + (m0 + 16 * q4) * LDP + PV + h * 128 + vcol; unsigned vv[16];
; #pragma unroll
;           for (int jj = 0; jj < 16; ++jj) vv[jj] = vp[(size_t)jj * LDP];
; #pragma unroll
;           for (int jj = 0; jj < 16; ++jj) asm volatile("" : "+v"(vv[jj]));
;           v4u w0, w1; w0.x = vv[0] | (vv[1] << 16); w0.y = vv[2] | (vv[3] << 16); w0.z = vv[4] | (vv[5] << 16); w0.w = vv[6] | (vv[7] << 16);
;           w1.x = vv[8] | (vv[9] << 16); w1.y = vv[10] | (vv[11] << 16); w1.z = vv[12] | (vv[13] << 16); w1.w = vv[14] | (vv[15] << 16);
;           *(LAS v4u*)(VT + vcol * RS + q4 * 32) = w0; *(LAS v4u*)(VT + vcol * RS + q4 * 32 + 16) = w1; }
;         __syncthreads();
;         float off = 0.f, tot = 0.f;
; #pragma unroll
;         for (int q2 = 0; q2 < 4; ++q2) { const float t = OFFS[(d * 4 + q2) * 64 + kk]; tot += t; if (d ? (q2 > qt) : (q2 < qt)) off += t; }
.LBB0_609:
	s_or_b64 exec, exec, s[0:1]
	v_ashrrev_i32_e32 v7, 7, v48
	v_lshlrev_b32_e32 v36, 4, v7
	v_ashrrev_i32_e32 v37, 31, v36
	v_lshl_add_u64 v[36:37], s[6:7], 0, v[36:37]
	v_mov_b64_e32 v[38:39], s[56:57]
	v_and_b32_e32 v5, 0x7f, v48
	v_mad_u64_u32 v[38:39], s[0:1], v36, s73, v[38:39]
	v_mad_i32_i24 v39, v37, s73, v39
	v_lshlrev_b32_e32 v2, 1, v5
	v_lshl_add_u64 v[36:37], v[38:39], 0, v[2:3]
	v_add_co_u32_e64 v38, s[6:7], s61, v36
	s_mov_b32 s0, 0x15000
	s_nop 0
	v_addc_co_u32_e64 v39, s[6:7], 0, v37, s[6:7]
	v_add_co_u32_e64 v40, s[6:7], s65, v36
	s_nop 1
	v_addc_co_u32_e64 v41, s[6:7], 0, v37, s[6:7]
	v_add_co_u32_e64 v42, s[6:7], s66, v36
	s_nop 1
	v_addc_co_u32_e64 v43, s[6:7], 0, v37, s[6:7]
	v_add_co_u32_e64 v44, s[6:7], s67, v36
	s_nop 1
	v_addc_co_u32_e64 v45, s[6:7], 0, v37, s[6:7]
	v_add_co_u32_e64 v46, s[6:7], s68, v36
	s_nop 1
	v_addc_co_u32_e64 v47, s[6:7], 0, v37, s[6:7]
	v_add_co_u32_e64 v68, s[6:7], s69, v36
	s_nop 1
	v_addc_co_u32_e64 v69, s[6:7], 0, v37, s[6:7]
	v_add_co_u32_e64 v70, s[6:7], s71, v36
	s_nop 1
	v_addc_co_u32_e64 v71, s[6:7], 0, v37, s[6:7]
	v_mov_b32_e32 v2, v160
	v_mov_b32_e32 v8, v161
	v_mov_b32_e32 v11, v162
	v_mov_b32_e32 v13, v163
	v_mov_b32_e32 v15, v164
	v_mov_b32_e32 v17, v165
	v_mov_b32_e32 v19, v166
	v_mov_b32_e32 v21, v167
	v_add_co_u32_e64 v38, s[6:7], s72, v36
	s_nop 1
	v_addc_co_u32_e64 v39, s[6:7], 0, v37, s[6:7]
	v_add_co_u32_e64 v40, s[6:7], s74, v36
	s_nop 1
	v_addc_co_u32_e64 v41, s[6:7], 0, v37, s[6:7]
	v_add_co_u32_e64 v42, s[6:7], s75, v36
	s_nop 1
	v_addc_co_u32_e64 v43, s[6:7], 0, v37, s[6:7]
	v_add_co_u32_e64 v44, s[6:7], s80, v36
	s_nop 1
	v_addc_co_u32_e64 v45, s[6:7], 0, v37, s[6:7]
	v_add_co_u32_e64 v46, s[6:7], s81, v36
	s_nop 1
	v_addc_co_u32_e64 v47, s[6:7], 0, v37, s[6:7]
	v_add_co_u32_e64 v68, s[6:7], s82, v36
	s_nop 1
	v_addc_co_u32_e64 v69, s[6:7], 0, v37, s[6:7]
	v_add_co_u32_e64 v70, s[6:7], s83, v36
	s_nop 1
	v_addc_co_u32_e64 v71, s[6:7], 0, v37, s[6:7]
	v_add_co_u32_e64 v36, s[6:7], s0, v36
	s_mov_b64 s[0:1], 0
	s_nop 0
	v_addc_co_u32_e64 v37, s[6:7], 0, v37, s[6:7]
	v_mov_b32_e32 v23, v168
	v_mov_b32_e32 v25, v169
	v_mov_b32_e32 v27, v170
	v_mov_b32_e32 v29, v171
	v_mov_b32_e32 v31, v172
	v_mov_b32_e32 v33, v173
	v_mov_b32_e32 v35, v174
	s_nop 0
	v_mov_b32_e32 v37, v175
	v_lshlrev_b32_e32 v46, 10, v49
	v_lshlrev_b32_e32 v39, 8, v51
	v_add_u32_e32 v40, s85, v46
	v_lshlrev_b32_e32 v36, 2, v50
	v_cndmask_b32_e32 v38, v9, v6, vcc
	v_add3_u32 v39, v40, v39, v36
	ds_write_b32 v39, v38
	s_waitcnt vmcnt(15)
	s_waitcnt vmcnt(14)
	s_waitcnt vmcnt(13)
	s_waitcnt vmcnt(12)
	s_waitcnt vmcnt(11)
	s_waitcnt vmcnt(10)
	s_waitcnt vmcnt(9)
	v_lshl_or_b32 v38, v8, 16, v2
	v_mul_u32_u24_e32 v2, 0x90, v5
	v_lshlrev_b32_e32 v5, 5, v7
	s_waitcnt vmcnt(8)
	v_lshl_or_b32 v39, v13, 16, v11
	v_lshl_or_b32 v40, v17, 16, v15
	v_lshl_or_b32 v41, v21, 16, v19
	v_add3_u32 v2, 0, v2, v5
	s_waitcnt vmcnt(7)
	s_waitcnt vmcnt(6)
	s_waitcnt vmcnt(5)
	s_waitcnt vmcnt(4)
	s_waitcnt vmcnt(3)
	s_waitcnt vmcnt(2)
	s_waitcnt vmcnt(1)
	s_waitcnt vmcnt(0)
	v_lshl_or_b32 v42, v25, 16, v23
	v_lshl_or_b32 v43, v29, 16, v27
	v_lshl_or_b32 v44, v33, 16, v31
	v_lshl_or_b32 v45, v37, 16, v35
	ds_write_b128 v2, v[38:41] offset:55296
	ds_write_b128 v2, v[42:45] offset:55312
	v_add_u32_e32 v2, s85, v36
	v_add_u32_e32 v2, v2, v46
	s_waitcnt lgkmcnt(0)
	s_barrier
	ds_read2st64_b32 v[38:39], v2 offset1:1
	v_cmp_eq_u32_e64 s[6:7], 0, v51
	s_and_saveexec_b64 s[8:9], s[4:5]
	s_xor_b64 s[12:13], exec, s[8:9]
	v_cmp_lt_u32_e64 s[8:9], 1, v51
	s_and_b64 s[0:1], s[8:9], exec
	s_or_saveexec_b64 s[8:9], s[12:13]
	s_waitcnt lgkmcnt(0)
	v_add_f32_e32 v7, 0, v38
	s_or_b64 s[12:13], vcc, s[6:7]
	v_cndmask_b32_e64 v8, v7, 0, s[12:13]
	v_mov_b32_e32 v5, v8
	s_xor_b64 exec, exec, s[8:9]
	s_andn2_b64 s[0:1], s[0:1], exec
	s_and_b64 s[12:13], s[6:7], exec
	v_mov_b32_e32 v5, 0
	s_or_b64 s[0:1], s[0:1], s[12:13]
	s_or_b64 exec, exec, s[8:9]
	s_and_saveexec_b64 s[8:9], s[0:1]
	v_add_f32_e32 v5, v39, v8
	s_or_b64 exec, exec, s[8:9]
	ds_read_b32 v8, v2 offset:512
	s_mov_b64 s[0:1], 0
	v_cmp_eq_u32_e64 s[8:9], 3, v51
	s_and_saveexec_b64 s[12:13], s[4:5]
	s_xor_b64 s[4:5], exec, s[12:13]
	s_cbranch_execnz .LBB0_621
	s_andn2_saveexec_b64 s[8:9], s[4:5]
	s_cbranch_execnz .LBB0_622
